# phase-1 sample-row unit: 7 K-steps of staged loads in flight, per-fragment waits
# speedup vs baseline: 1.0075x; 1.0060x over previous
.LBB0_579:
	s_lshr_b32 s6, s15, 2
	s_and_b32 s3, s15, 7
	s_and_b32 s2, s12, 0xc0
	s_and_b32 s6, s6, 0x3fffff8
	s_bitset1_b32 s2, 14
	s_or_b32 s3, s6, s3
	s_lshl_b32 s3, s3, 6
	v_add_lshl_u32 v10, s2, v1, 11
	v_lshl_add_u64 v[24:25], v[12:13], 0, v[10:11]
	v_add_lshl_u32 v10, s3, v1, 11
	v_lshl_add_u64 v[116:117], v[14:15], 0, v[10:11]
	global_load_dwordx4 v[118:121], v[24:25], off
	global_load_dwordx4 v[122:125], v[24:25], off offset:128
	global_load_dwordx4 v[126:129], v[116:117], off
	global_load_dwordx4 v[130:133], v[116:117], off offset:128
	global_load_dwordx4 v[134:137], v[24:25], off offset:256
	global_load_dwordx4 v[138:141], v[24:25], off offset:384
	global_load_dwordx4 v[142:145], v[116:117], off offset:256
	global_load_dwordx4 v[146:149], v[116:117], off offset:384
	global_load_dwordx4 v[150:153], v[24:25], off offset:512
	global_load_dwordx4 v[158:161], v[24:25], off offset:640
	global_load_dwordx4 v[164:167], v[116:117], off offset:512
	global_load_dwordx4 v[168:171], v[116:117], off offset:640
	global_load_dwordx4 v[172:175], v[24:25], off offset:768
	global_load_dwordx4 v[176:179], v[24:25], off offset:896
	global_load_dwordx4 v[180:183], v[116:117], off offset:768
	global_load_dwordx4 v[184:187], v[116:117], off offset:896
	global_load_dwordx4 v[188:191], v[24:25], off offset:1024
	global_load_dwordx4 v[192:195], v[24:25], off offset:1152
	global_load_dwordx4 v[196:199], v[116:117], off offset:1024
	global_load_dwordx4 v[206:209], v[116:117], off offset:1152
	global_load_dwordx4 v[210:213], v[24:25], off offset:1280
	global_load_dwordx4 v[214:217], v[24:25], off offset:1408
	global_load_dwordx4 v[218:221], v[116:117], off offset:1280
	global_load_dwordx4 v[222:225], v[116:117], off offset:1408
	global_load_dwordx4 v[226:229], v[24:25], off offset:1536
	global_load_dwordx4 v[230:233], v[24:25], off offset:1664
	global_load_dwordx4 v[234:237], v[116:117], off offset:1536
	global_load_dwordx4 v[238:241], v[116:117], off offset:1664
	s_mov_b64 s[10:11], -1
	s_waitcnt vmcnt(27)
	ds_write_b128 v26, v[118:121]
	s_waitcnt vmcnt(26)
	ds_write_b128 v26, v[122:125] offset:128
	s_waitcnt vmcnt(25)
	ds_write_b128 v26, v[126:129] offset:34816
	s_waitcnt vmcnt(24)
	ds_write_b128 v26, v[130:133] offset:34944
	s_waitcnt lgkmcnt(0)
	s_barrier
	ds_read_b128 v[2:5], v33 offset:34816
	ds_read_b128 v[6:9], v33 offset:43520
	ds_read_b128 v[16:19], v28
	ds_read_b128 v[20:23], v28 offset:64
	ds_read_b128 v[84:87], v33 offset:34880
	global_load_dwordx4 v[118:121], v[24:25], off offset:1792
	global_load_dwordx4 v[122:125], v[24:25], off offset:1920
	ds_read_b128 v[96:99], v33 offset:43584
	s_waitcnt lgkmcnt(3)
	v_mfma_f32_16x16x32_bf16 v[2:5], v[2:5], v[16:19], 0
	v_mfma_f32_16x16x32_bf16 v[6:9], v[6:9], v[16:19], 0
	global_load_dwordx4 v[126:129], v[116:117], off offset:1792
	global_load_dwordx4 v[130:133], v[116:117], off offset:1920
	ds_read_b128 v[104:107], v33 offset:34944
	s_waitcnt lgkmcnt(2)
	v_mfma_f32_16x16x32_bf16 v[2:5], v[84:87], v[20:23], v[2:5]
	ds_read_b128 v[84:87], v33 offset:43648
	ds_read_b128 v[108:111], v28 offset:128
	ds_read_b128 v[112:115], v28 offset:192
	s_waitcnt lgkmcnt(4)
	v_mfma_f32_16x16x32_bf16 v[6:9], v[96:99], v[20:23], v[6:9]
	ds_read_b128 v[20:23], v33 offset:35008
	ds_read_b128 v[96:99], v33 offset:43712
	s_waitcnt vmcnt(27)
	ds_write_b128 v26, v[134:137] offset:17408
	s_waitcnt vmcnt(26)
	ds_write_b128 v26, v[138:141] offset:17536
	s_waitcnt vmcnt(25)
	ds_write_b128 v26, v[142:145] offset:52224
	s_waitcnt vmcnt(24)
	ds_write_b128 v26, v[146:149] offset:52352
	s_waitcnt lgkmcnt(7)
	v_mfma_f32_16x16x32_bf16 v[2:5], v[104:107], v[108:111], v[2:5]
	s_waitcnt lgkmcnt(0)
	s_barrier
	v_mfma_f32_16x16x32_bf16 v[6:9], v[84:87], v[108:111], v[6:9]
	v_mfma_f32_16x16x32_bf16 v[2:5], v[20:23], v[112:115], v[2:5]
	ds_read_b128 v[20:23], v30 offset:52224
	ds_read_b128 v[36:39], v30 offset:60928
	ds_read_b128 v[40:43], v29
	ds_read_b128 v[44:47], v29 offset:64
	ds_read_b128 v[48:51], v30 offset:52288
	v_mfma_f32_16x16x32_bf16 v[6:9], v[96:99], v[112:115], v[6:9]
	s_waitcnt lgkmcnt(2)
	v_mfma_f32_16x16x32_bf16 v[2:5], v[20:23], v[40:43], v[2:5]
	ds_read_b128 v[96:99], v30 offset:60992
	v_mfma_f32_16x16x32_bf16 v[6:9], v[36:39], v[40:43], v[6:9]
	ds_read_b128 v[104:107], v30 offset:52352
	s_waitcnt lgkmcnt(2)
	v_mfma_f32_16x16x32_bf16 v[2:5], v[48:51], v[44:47], v[2:5]
	ds_read_b128 v[48:51], v30 offset:61056
	ds_read_b128 v[108:111], v29 offset:128
	ds_read_b128 v[112:115], v29 offset:192
	s_waitcnt lgkmcnt(4)
	v_mfma_f32_16x16x32_bf16 v[6:9], v[96:99], v[44:47], v[6:9]
	ds_read_b128 v[44:47], v30 offset:52416
	ds_read_b128 v[96:99], v30 offset:61120
	s_waitcnt vmcnt(23)
	ds_write_b128 v26, v[150:153]
	s_waitcnt vmcnt(22)
	ds_write_b128 v26, v[158:161] offset:128
	s_waitcnt vmcnt(21)
	ds_write_b128 v26, v[164:167] offset:34816
	s_waitcnt vmcnt(20)
	ds_write_b128 v26, v[168:171] offset:34944
	s_waitcnt lgkmcnt(7)
	v_mfma_f32_16x16x32_bf16 v[2:5], v[104:107], v[108:111], v[2:5]
	s_waitcnt lgkmcnt(0)
	s_barrier
	v_mfma_f32_16x16x32_bf16 v[6:9], v[48:51], v[108:111], v[6:9]
	v_mfma_f32_16x16x32_bf16 v[2:5], v[44:47], v[112:115], v[2:5]
	ds_read_b128 v[44:47], v33 offset:34816
	ds_read_b128 v[48:51], v33 offset:43520
	ds_read_b128 v[52:55], v28
	ds_read_b128 v[56:59], v28 offset:64
	ds_read_b128 v[60:63], v33 offset:34880
	v_mfma_f32_16x16x32_bf16 v[6:9], v[96:99], v[112:115], v[6:9]
	s_waitcnt lgkmcnt(2)
	v_mfma_f32_16x16x32_bf16 v[2:5], v[44:47], v[52:55], v[2:5]
	ds_read_b128 v[96:99], v33 offset:43584
	v_mfma_f32_16x16x32_bf16 v[6:9], v[48:51], v[52:55], v[6:9]
	ds_read_b128 v[104:107], v33 offset:34944
	s_waitcnt lgkmcnt(2)
	v_mfma_f32_16x16x32_bf16 v[2:5], v[60:63], v[56:59], v[2:5]
	ds_read_b128 v[60:63], v33 offset:43648
	ds_read_b128 v[108:111], v28 offset:128
	ds_read_b128 v[112:115], v28 offset:192
	s_waitcnt lgkmcnt(4)
	v_mfma_f32_16x16x32_bf16 v[6:9], v[96:99], v[56:59], v[6:9]
	ds_read_b128 v[56:59], v33 offset:35008
	ds_read_b128 v[96:99], v33 offset:43712
	s_waitcnt vmcnt(19)
	ds_write_b128 v26, v[172:175] offset:17408
	s_waitcnt vmcnt(18)
	ds_write_b128 v26, v[176:179] offset:17536
	s_waitcnt vmcnt(17)
	ds_write_b128 v26, v[180:183] offset:52224
	s_waitcnt vmcnt(16)
	ds_write_b128 v26, v[184:187] offset:52352
	s_waitcnt lgkmcnt(7)
	v_mfma_f32_16x16x32_bf16 v[2:5], v[104:107], v[108:111], v[2:5]
	s_waitcnt lgkmcnt(0)
	s_barrier
	v_mfma_f32_16x16x32_bf16 v[2:5], v[56:59], v[112:115], v[2:5]
	ds_read_b128 v[56:59], v30 offset:52224
	v_mfma_f32_16x16x32_bf16 v[6:9], v[60:63], v[108:111], v[6:9]
	ds_read_b128 v[60:63], v29
	ds_read_b128 v[68:71], v29 offset:64
	ds_read_b128 v[72:75], v30 offset:52288
	v_mfma_f32_16x16x32_bf16 v[6:9], v[96:99], v[112:115], v[6:9]
	s_waitcnt lgkmcnt(2)
	v_mfma_f32_16x16x32_bf16 v[2:5], v[56:59], v[60:63], v[2:5]
	ds_read_b128 v[56:59], v30 offset:60928
	ds_read_b128 v[76:79], v30 offset:60992
	s_waitcnt lgkmcnt(1)
	v_mfma_f32_16x16x32_bf16 v[6:9], v[56:59], v[60:63], v[6:9]
	ds_read_b128 v[56:59], v30 offset:52352
	v_mfma_f32_16x16x32_bf16 v[2:5], v[72:75], v[68:71], v[2:5]
	s_waitcnt lgkmcnt(1)
	v_mfma_f32_16x16x32_bf16 v[6:9], v[76:79], v[68:71], v[6:9]
	ds_read_b128 v[60:63], v29 offset:128
	ds_read_b128 v[68:71], v29 offset:192
	ds_read_b128 v[72:75], v30 offset:52416
	s_waitcnt lgkmcnt(2)
	v_mfma_f32_16x16x32_bf16 v[2:5], v[56:59], v[60:63], v[2:5]
	ds_read_b128 v[56:59], v30 offset:61056
	ds_read_b128 v[76:79], v30 offset:61120
	s_waitcnt lgkmcnt(1)
	v_mfma_f32_16x16x32_bf16 v[6:9], v[56:59], v[60:63], v[6:9]
	s_waitcnt vmcnt(15)
	ds_write_b128 v26, v[188:191]
	s_waitcnt vmcnt(14)
	ds_write_b128 v26, v[192:195] offset:128
	s_waitcnt vmcnt(13)
	ds_write_b128 v26, v[196:199] offset:34816
	s_waitcnt vmcnt(12)
	ds_write_b128 v26, v[206:209] offset:34944
	s_waitcnt lgkmcnt(0)
	s_barrier
	ds_read_b128 v[16:19], v33 offset:34816
	v_mfma_f32_16x16x32_bf16 v[2:5], v[72:75], v[68:71], v[2:5]
	v_mfma_f32_16x16x32_bf16 v[6:9], v[76:79], v[68:71], v[6:9]
	ds_read_b128 v[68:71], v28
	ds_read_b128 v[72:75], v28 offset:64
	ds_read_b128 v[76:79], v33 offset:34880
	s_waitcnt lgkmcnt(2)
	v_mfma_f32_16x16x32_bf16 v[2:5], v[16:19], v[68:71], v[2:5]
	ds_read_b128 v[16:19], v33 offset:43520
	ds_read_b128 v[88:91], v33 offset:43584
	s_waitcnt lgkmcnt(1)
	v_mfma_f32_16x16x32_bf16 v[6:9], v[16:19], v[68:71], v[6:9]
	ds_read_b128 v[16:19], v33 offset:34944
	v_mfma_f32_16x16x32_bf16 v[2:5], v[76:79], v[72:75], v[2:5]
	ds_read_b128 v[68:71], v33 offset:43648
	ds_read_b128 v[76:79], v28 offset:128
	ds_read_b128 v[92:95], v28 offset:192
	s_waitcnt lgkmcnt(4)
	v_mfma_f32_16x16x32_bf16 v[6:9], v[88:91], v[72:75], v[6:9]
	ds_read_b128 v[72:75], v33 offset:35008
	ds_read_b128 v[88:91], v33 offset:43712
	s_waitcnt vmcnt(11)
	ds_write_b128 v26, v[210:213] offset:17408
	s_waitcnt vmcnt(10)
	ds_write_b128 v26, v[214:217] offset:17536
	s_waitcnt vmcnt(9)
	ds_write_b128 v26, v[218:221] offset:52224
	s_waitcnt vmcnt(8)
	ds_write_b128 v26, v[222:225] offset:52352
	s_waitcnt lgkmcnt(7)
	v_mfma_f32_16x16x32_bf16 v[2:5], v[16:19], v[76:79], v[2:5]
	s_waitcnt lgkmcnt(0)
	s_barrier
	ds_read_b128 v[16:19], v30 offset:52224
	v_mfma_f32_16x16x32_bf16 v[6:9], v[68:71], v[76:79], v[6:9]
	ds_read_b128 v[20:23], v29
	ds_read_b128 v[36:39], v29 offset:64
	ds_read_b128 v[40:43], v30 offset:52288
	v_mfma_f32_16x16x32_bf16 v[2:5], v[72:75], v[92:95], v[2:5]
	v_mfma_f32_16x16x32_bf16 v[6:9], v[88:91], v[92:95], v[6:9]
	s_waitcnt lgkmcnt(2)
	v_mfma_f32_16x16x32_bf16 v[2:5], v[16:19], v[20:23], v[2:5]
	ds_read_b128 v[16:19], v30 offset:60928
	ds_read_b128 v[68:71], v30 offset:60992
	s_waitcnt lgkmcnt(1)
	v_mfma_f32_16x16x32_bf16 v[6:9], v[16:19], v[20:23], v[6:9]
	ds_read_b128 v[16:19], v30 offset:52352
	v_mfma_f32_16x16x32_bf16 v[2:5], v[40:43], v[36:39], v[2:5]
	s_waitcnt lgkmcnt(1)
	v_mfma_f32_16x16x32_bf16 v[6:9], v[68:71], v[36:39], v[6:9]
	ds_read_b128 v[20:23], v29 offset:128
	ds_read_b128 v[36:39], v29 offset:192
	ds_read_b128 v[40:43], v30 offset:52416
	s_waitcnt lgkmcnt(2)
	v_mfma_f32_16x16x32_bf16 v[2:5], v[16:19], v[20:23], v[2:5]
	ds_read_b128 v[16:19], v30 offset:61056
	ds_read_b128 v[68:71], v30 offset:61120
	s_waitcnt vmcnt(7)
	ds_write_b128 v26, v[226:229]
	s_waitcnt vmcnt(6)
	ds_write_b128 v26, v[230:233] offset:128
	s_waitcnt vmcnt(5)
	ds_write_b128 v26, v[234:237] offset:34816
	s_waitcnt vmcnt(4)
	ds_write_b128 v26, v[238:241] offset:34944
	s_waitcnt lgkmcnt(0)
	v_mfma_f32_16x16x32_bf16 v[6:9], v[16:19], v[20:23], v[6:9]
	s_barrier
	ds_read_b128 v[16:19], v33 offset:34816
	v_mfma_f32_16x16x32_bf16 v[2:5], v[40:43], v[36:39], v[2:5]
	v_mfma_f32_16x16x32_bf16 v[6:9], v[68:71], v[36:39], v[6:9]
	ds_read_b128 v[20:23], v28
	ds_read_b128 v[36:39], v28 offset:64
	ds_read_b128 v[40:43], v33 offset:34880
	s_waitcnt lgkmcnt(2)
	v_mfma_f32_16x16x32_bf16 v[2:5], v[16:19], v[20:23], v[2:5]
	ds_read_b128 v[16:19], v33 offset:43520
	ds_read_b128 v[44:47], v33 offset:43584
	s_waitcnt lgkmcnt(1)
	v_mfma_f32_16x16x32_bf16 v[6:9], v[16:19], v[20:23], v[6:9]
	ds_read_b128 v[16:19], v33 offset:34944
	v_mfma_f32_16x16x32_bf16 v[2:5], v[40:43], v[36:39], v[2:5]
	s_waitcnt lgkmcnt(1)
	v_mfma_f32_16x16x32_bf16 v[6:9], v[44:47], v[36:39], v[6:9]
	ds_read_b128 v[20:23], v28 offset:128
	ds_read_b128 v[36:39], v28 offset:192
	ds_read_b128 v[40:43], v33 offset:35008
	s_waitcnt lgkmcnt(2)
	v_mfma_f32_16x16x32_bf16 v[2:5], v[16:19], v[20:23], v[2:5]
	ds_read_b128 v[16:19], v33 offset:43648
	ds_read_b128 v[44:47], v33 offset:43712
	s_waitcnt vmcnt(3)
	ds_write_b128 v26, v[118:121] offset:17408
	s_waitcnt vmcnt(2)
	ds_write_b128 v26, v[122:125] offset:17536
	s_waitcnt vmcnt(1)
	ds_write_b128 v26, v[126:129] offset:52224
	s_waitcnt vmcnt(0)
	ds_write_b128 v26, v[130:133] offset:52352
	s_waitcnt lgkmcnt(0)
	v_mfma_f32_16x16x32_bf16 v[6:9], v[16:19], v[20:23], v[6:9]
	s_barrier
	ds_read_b128 v[16:19], v30 offset:52224
	v_mfma_f32_16x16x32_bf16 v[2:5], v[40:43], v[36:39], v[2:5]
	v_mfma_f32_16x16x32_bf16 v[6:9], v[44:47], v[36:39], v[6:9]
	ds_read_b128 v[20:23], v29
	ds_read_b128 v[36:39], v29 offset:64
	ds_read_b128 v[40:43], v30 offset:52288
	s_waitcnt lgkmcnt(2)
	v_mfma_f32_16x16x32_bf16 v[2:5], v[16:19], v[20:23], v[2:5]
	ds_read_b128 v[16:19], v30 offset:60928
	ds_read_b128 v[44:47], v30 offset:60992
	s_waitcnt lgkmcnt(1)
	v_mfma_f32_16x16x32_bf16 v[6:9], v[16:19], v[20:23], v[6:9]
	ds_read_b128 v[16:19], v30 offset:52352
	v_mfma_f32_16x16x32_bf16 v[2:5], v[40:43], v[36:39], v[2:5]
	s_waitcnt lgkmcnt(1)
	v_mfma_f32_16x16x32_bf16 v[6:9], v[44:47], v[36:39], v[6:9]
	ds_read_b128 v[20:23], v29 offset:128
	ds_read_b128 v[36:39], v29 offset:192
	ds_read_b128 v[40:43], v30 offset:52416
	s_waitcnt lgkmcnt(2)
	v_mfma_f32_16x16x32_bf16 v[2:5], v[16:19], v[20:23], v[2:5]
	ds_read_b128 v[16:19], v30 offset:61056
	ds_read_b128 v[44:47], v30 offset:61120
	s_waitcnt lgkmcnt(0)
	s_barrier
	v_mfma_f32_16x16x32_bf16 v[16:19], v[16:19], v[20:23], v[6:9]
	v_mov_b32_e32 v23, v11
	v_mov_b32_e32 v21, v11
	v_mfma_f32_16x16x32_bf16 v[6:9], v[40:43], v[36:39], v[2:5]
	v_mfma_f32_16x16x32_bf16 v[2:5], v[44:47], v[36:39], v[16:19]
	s_nop 3
	v_add_u32_e32 v17, s2, v27
	s_lshr_b32 s2, s15, 5
	s_cmp_lg_u32 s2, 3
	s_cselect_b64 s[6:7], -1, 0
	v_mul_u32_u24_e32 v10, 0xc00, v17
	s_cmp_eq_u32 s2, 2
	v_lshl_add_u32 v22, v17, 11, v34
	v_lshlrev_b32_e32 v20, 10, v17
	v_add_u32_e32 v17, 0xffffc000, v17
	s_cselect_b32 s18, s14, 0x2047800
	v_lshrrev_b32_e32 v17, 5, v17
	s_cmp_gt_u32 s15, 31
	v_or_b32_e32 v16, s3, v31
	v_mad_u32_u24 v18, v17, 15, v32
	v_mov_b32_e32 v19, v11
	s_cselect_b64 s[2:3], -1, 0
	v_cndmask_b32_e64 v17, 0, 1, s[6:7]
	v_lshlrev_b64 v[18:19], 11, v[18:19]
	s_and_b64 vcc, exec, s[2:3]
	v_cmp_ne_u32_e64 s[6:7], 1, v17
	s_cbranch_vccz .LBB0_595
	s_and_b64 vcc, exec, s[6:7]
	v_and_b32_e32 v24, 0x1dc, v16
	s_cbranch_vccnz .LBB0_582
	s_lshl_b32 s10, s18, 2
	v_lshl_add_u64 v[38:39], s[94:95], 0, v[10:11]
	v_mov_b32_e32 v17, v11
	s_add_u32 s10, s84, s10
	v_cvt_pk_bf16_f32 v36, v6, v7
	v_cvt_pk_bf16_f32 v37, v8, v9
	v_lshl_add_u64 v[38:39], v[16:17], 1, v[38:39]
	s_addc_u32 s11, s85, 0
	global_store_dwordx2 v[38:39], v[36:37], off
	v_lshl_add_u64 v[36:37], s[10:11], 0, v[22:23]
	v_lshlrev_b32_e32 v38, 2, v24
	v_mov_b32_e32 v39, v11
	v_lshl_add_u64 v[36:37], v[36:37], 0, v[38:39]
	s_mov_b64 s[10:11], 0
	global_store_dwordx4 v[36:37], v[6:9], off nt
